# out-proj loop tail: MFMA-only waves L2-prefetch the first 16-row quarter of the tile's residual (iterations 27-28) so the LayerNorm epilogue's first wait is an L2 hit
# baseline (speedup 1.0000x reference)
; DI void unit_O(const Params& p, char* lds, int l, int tile, int glu_tiles, int tile_b) {
;     ...
;     const bf16_t* xbres = WS_PTR(const bf16_t, OFF_XB1) + ((size_t)((tile >> 1) * 32) * 128 + (tile & 1) * 64) * 32;
;     auto issue_x = [&](int half) {
;         if (l == 0) {
; #pragma unroll 1
;             for (int i = 0; i < 16; ++i) {
;                 const int pc = (wid * 16 + i + xrot) & 127, row = pc >> 2, phys = (pc & 3) * 64 + lane, logical = phys ^ (row & 15);
;                 __builtin_amdgcn_global_load_lds((const unsigned*)(xres + (r0 + half * 32 + row) * 1024 + logical * 4), (unsigned*)(XR + pc * 1024 + lane * 16), 16, 0, 0);
;             }
;         } else {
; #pragma unroll 1
;             for (int i = 0; i < 8; ++i) {
;                 const int pc = (wid * 8 + i + (xrot >> 1)) & 63, kt = pc >> 1, sub = pc & 1;
;                 __builtin_amdgcn_global_load_lds((const unsigned*)(xbres + ((size_t)kt * 128 + half * 32) * 32 + sub * 512 + lane * 8), (unsigned*)(XR + pc * 1024 + lane * 16), 16, 0, 0);
.Lpo1_ypf_skip:
	s_sub_u32 s94, s9, 27
	s_cmp_lt_u32 s94, 2
	s_cbranch_scc0 .Lpo1_epf_skip
	s_cmp_lg_u64 s[10:11], 0
	s_cbranch_scc1 .Lpo1_epf_l1
	s_lshl_b32 s94, s94, 15
	s_lshl_b32 s92, s34, 18
	s_add_u32 s94, s94, s92
	s_add_u32 s92, s52, s94
	s_addc_u32 s93, s53, 0
	v_lshlrev_b32_e32 v199, 7, v246
	global_load_dword v247, v199, s[92:93]
	s_branch .Lpo1_epf_skip
.Lpo1_epf_l1:
	s_cmp_lg_u32 s94, 0
	s_cbranch_scc1 .Lpo1_epf_skip
	s_lshr_b32 s94, s34, 1
	s_lshl_b32 s94, s94, 18
	s_and_b32 s92, s34, 1
	s_lshl_b32 s92, s92, 12
	s_add_u32 s94, s94, s92
	s_add_u32 s92, s56, s94
	s_addc_u32 s93, s57, 0
	v_lshrrev_b32_e32 v199, 3, v246
	v_and_b32_e32 v247, 7, v246
	v_lshlrev_b32_e32 v247, 7, v247
	v_lshl_or_b32 v199, v199, 13, v247
	global_load_dword v247, v199, s[92:93]

; DI void unit_O(const Params& p, char* lds, int l, int tile, int glu_tiles, int tile_b) {
;     ...
;     const bf16_t* xbres = WS_PTR(const bf16_t, OFF_XB1) + ((size_t)((tile >> 1) * 32) * 128 + (tile & 1) * 64) * 32;
;     auto issue_x = [&](int half) {
;         if (l == 0) {
; #pragma unroll 1
;             for (int i = 0; i < 16; ++i) {
;                 const int pc = (wid * 16 + i + xrot) & 127, row = pc >> 2, phys = (pc & 3) * 64 + lane, logical = phys ^ (row & 15);
;                 __builtin_amdgcn_global_load_lds((const unsigned*)(xres + (r0 + half * 32 + row) * 1024 + logical * 4), (unsigned*)(XR + pc * 1024 + lane * 16), 16, 0, 0);
;             }
;         } else {
; #pragma unroll 1
;             for (int i = 0; i < 8; ++i) {
;                 const int pc = (wid * 8 + i + (xrot >> 1)) & 63, kt = pc >> 1, sub = pc & 1;
;                 __builtin_amdgcn_global_load_lds((const unsigned*)(xbres + ((size_t)kt * 128 + half * 32) * 32 + sub * 512 + lane * 8), (unsigned*)(XR + pc * 1024 + lane * 16), 16, 0, 0);
.Lpo2_ypf_skip:
	s_sub_u32 s94, s29, 27
	s_cmp_lt_u32 s94, 2
	s_cbranch_scc0 .Lpo2_epf_skip
	s_cmp_lg_u64 s[10:11], 0
	s_cbranch_scc1 .Lpo2_epf_l1
	s_lshl_b32 s94, s94, 15
	s_lshl_b32 s92, s48, 18
	s_add_u32 s94, s94, s92
	s_add_u32 s92, s52, s94
	s_addc_u32 s93, s53, 0
	v_lshlrev_b32_e32 v199, 7, v246
	global_load_dword v247, v199, s[92:93]
	s_branch .Lpo2_epf_skip
.Lpo2_epf_l1:
	s_cmp_lg_u32 s94, 0
	s_cbranch_scc1 .Lpo2_epf_skip
	s_lshr_b32 s94, s48, 1
	s_lshl_b32 s94, s94, 18
	s_and_b32 s92, s48, 1
	s_lshl_b32 s92, s92, 12
	s_add_u32 s94, s94, s92
	s_add_u32 s92, s56, s94
	s_addc_u32 s93, s57, 0
	v_lshrrev_b32_e32 v199, 3, v246
	v_and_b32_e32 v247, 7, v246
	v_lshlrev_b32_e32 v247, 7, v247
	v_lshl_or_b32 v199, v199, 13, v247
	global_load_dword v247, v199, s[92:93]
